# NA first-step copies: tile staging (waits, 4 LDS writes, next loads) moved ahead of the P.V fragment reads in the computing path
# baseline (speedup 1.0000x reference)
; #define NA_VR(D) do { vl[D][0] = tr_read<v_rd_off(D, KS0, 0)>(vb); vh[D][0] = tr_read<v_rd_off(D, KS0, 1)>(vb); vl[D][1] = tr_read<v_rd_off(D, KS0 + 1, 0)>(vb); vh[D][1] = tr_read<v_rd_off(D, KS0 + 1, 1)>(vb); \
;     vl[D][2] = tr_read<v_rd_off(D, KS0 + 2, 0)>(vb); vh[D][2] = tr_read<v_rd_off(D, KS0 + 2, 1)>(vb); } while (0)
; template <int M> __device__ __forceinline__ void na_tile(f32x16 (&o)[4], float& m_reg, float& l_reg, f32x16& p0, f32x16& p1, int vb, const char* blane, int mbase, float* al_l, int r32, int hi) {
;   bf16x8 pa, pb, pc;
;   if constexpr (M == 0) { NA_BODY(p0, p1, 0, 0, 1, 4)  ATT_PK4(p0, 0, pa); ATT_PK4(p0, 8, pb); ATT_PK4(p1, 0, pc); }
;   else                  { NA_BODY(p1, p0, 12, 1, 0, 8) ATT_PK4(p0, 8, pa); ATT_PK4(p1, 0, pb); ATT_PK4(p1, 8, pc); }
;   constexpr int KS0 = (M == 0) ? 0 : 1;
;   s16x4 vl[4][3], vh[4][3];
;     ...
;   NA_VR(0); NA_VR(1); NA_PV(0, 6); NA_VR(2); NA_PV(1, 6); NA_VR(3); NA_PV(2, 6); NA_PV(3, 0);
.LBB0_526:
	v_sub_f32_e32 v94, v202, v198
	v_exp_f32_e32 v94, v94
	v_sub_f32_e32 v96, v201, v198
	v_exp_f32_e32 v96, v96
	v_sub_f32_e32 v97, v200, v198
	v_exp_f32_e32 v97, v97
	v_sub_f32_e32 v102, v199, v198
	v_exp_f32_e32 v102, v102
	v_sub_f32_e32 v101, v101, v198
	v_add_f32_e32 v95, 0, v94
	v_exp_f32_e32 v101, v101
	v_sub_f32_e32 v100, v100, v198
	v_add_f32_e32 v95, v96, v95
	v_exp_f32_e32 v100, v100
	v_sub_f32_e32 v99, v99, v198
	v_add_f32_e32 v95, v97, v95
	v_exp_f32_e32 v99, v99
	v_sub_f32_e32 v98, v98, v198
	v_add_f32_e32 v95, v102, v95
	v_exp_f32_e32 v98, v98
	v_sub_f32_e32 v93, v93, v198
	v_add_f32_e32 v95, v101, v95
	v_exp_f32_e32 v103, v93
	v_add_f32_e32 v95, v100, v95
	v_add_f32_e32 v95, v99, v95
	v_add_f32_e32 v95, v98, v95
	v_sub_f32_e32 v92, v92, v198
	v_add_f32_e32 v93, v103, v95
	v_exp_f32_e32 v95, v92
	v_sub_f32_e32 v91, v91, v198
	v_exp_f32_e32 v104, v91
	v_sub_f32_e32 v90, v90, v198
	v_exp_f32_e32 v105, v90
	v_sub_f32_e32 v89, v89, v198
	v_exp_f32_e32 v106, v89
	v_sub_f32_e32 v88, v88, v198
	v_add_f32_e32 v92, v95, v93
	v_exp_f32_e32 v107, v88
	v_sub_f32_e32 v87, v87, v198
	v_add_f32_e32 v91, v104, v92
	v_exp_f32_e32 v108, v87
	v_sub_f32_e32 v86, v86, v198
	v_add_f32_e32 v90, v105, v91
	v_exp_f32_e32 v109, v86
	v_sub_f32_e32 v82, v82, v198
	v_add_f32_e32 v89, v106, v90
	v_exp_f32_e32 v82, v82
	v_sub_f32_e32 v83, v83, v198
	v_add_f32_e32 v88, v107, v89
	v_exp_f32_e32 v83, v83
	v_sub_f32_e32 v84, v84, v198
	v_add_f32_e32 v87, v108, v88
	v_exp_f32_e32 v84, v84
	v_sub_f32_e32 v85, v85, v198
	v_add_f32_e32 v86, v109, v87
	v_exp_f32_e32 v85, v85
	v_add_f32_e32 v86, v82, v86
	v_add_f32_e32 v86, v83, v86
	v_add_f32_e32 v86, v84, v86
	v_add_f32_e32 v86, v85, v86
	v_mov_b32_e32 v87, v86
	s_nop 1
	v_permlane32_swap_b32_e32 v86, v87
	v_add_f32_e32 v86, v86, v87
	v_add_f32_e32 v169, v169, v86
	v_cvt_pk_bf16_f32 v90, v196, v196
	v_cvt_pk_bf16_f32 v91, v196, v147
	v_cvt_pk_bf16_f32 v92, v82, v83
	v_cvt_pk_bf16_f32 v93, v84, v85
	v_cvt_pk_bf16_f32 v86, v94, v96
	v_cvt_pk_bf16_f32 v87, v97, v102
	v_cvt_pk_bf16_f32 v88, v101, v100
	v_cvt_pk_bf16_f32 v89, v99, v98
	v_cvt_pk_bf16_f32 v82, v103, v95
	v_cvt_pk_bf16_f32 v83, v104, v105
	v_cvt_pk_bf16_f32 v84, v106, v107
	v_cvt_pk_bf16_f32 v85, v108, v109
	s_add_i32 s51, s2, -2
	s_cmp_lt_i32 s51, s83
	s_cselect_b64 s[64:65], -1, 0
	s_cmp_ge_i32 s51, s83
	s_cbranch_scc1 .Lna_stgA_done
	s_cmp_gt_i32 s51, s72
	s_waitcnt vmcnt(3)
	ds_write_b128 v165, v[130:133] offset:16384
	s_waitcnt vmcnt(1)
	ds_write_b128 v166, v[138:141] offset:16384
	ds_write_b128 v163, v[134:137] offset:49152
	s_waitcnt vmcnt(0)
	ds_write_b128 v164, v[142:145] offset:49152
	s_cbranch_scc1 .Lna_stgA_done
	v_lshl_add_u64 v[246:247], v[154:155], 0, v[146:147]
	v_add_co_u32_e32 v246, vcc, 0x1000, v246
	v_lshl_add_u64 v[254:255], v[152:153], 0, v[146:147]
	s_nop 0
	v_addc_co_u32_e32 v247, vcc, 0, v247, vcc
	v_add_co_u32_e32 v254, vcc, 0x1000, v254
	s_nop 1
	v_addc_co_u32_e32 v255, vcc, 0, v255, vcc
	global_load_dwordx4 v[130:133], v[246:247], off offset:2048
	global_load_dwordx4 v[134:137], v[246:247], off
	global_load_dwordx4 v[138:141], v[254:255], off offset:2048
	global_load_dwordx4 v[142:145], v[254:255], off
.Lna_stgA_done:
	ds_read_b64_tr_b16 v[94:95], v168 offset:0x1000
	ds_read_b64_tr_b16 v[96:97], v168 offset:0x1800
	ds_read_b64_tr_b16 v[98:99], v168 offset:0x2000
	ds_read_b64_tr_b16 v[100:101], v168 offset:0x2800
	ds_read_b64_tr_b16 v[102:103], v168 offset:0x3000
	ds_read_b64_tr_b16 v[104:105], v168 offset:0x3800
	ds_read_b64_tr_b16 v[106:107], v168 offset:0x1200
	s_nop 0
	v_permlane32_swap_b32_e32 v90, v92
	v_permlane32_swap_b32_e32 v91, v93
	ds_read_b64_tr_b16 v[108:109], v168 offset:0x1a00
	ds_read_b64_tr_b16 v[110:111], v168 offset:0x2200
	ds_read_b64_tr_b16 v[112:113], v168 offset:0x2a00
	ds_read_b64_tr_b16 v[200:201], v168 offset:0x3200
	ds_read_b64_tr_b16 v[202:203], v168 offset:0x3a00
	s_waitcnt lgkmcnt(6)
	v_permlane32_swap_b32_e32 v86, v88
	s_nop 0
	v_mfma_f32_32x32x16_bf16 v[66:81], v[90:93], v[94:97], v[66:81]
	v_permlane32_swap_b32_e32 v87, v89
	v_permlane32_swap_b32_e32 v82, v84
	v_permlane32_swap_b32_e32 v83, v85
	ds_read_b64_tr_b16 v[94:95], v168 offset:0x1400
	v_mfma_f32_32x32x16_bf16 v[66:81], v[86:89], v[98:101], v[66:81]
	ds_read_b64_tr_b16 v[96:97], v168 offset:0x1c00
	ds_read_b64_tr_b16 v[98:99], v168 offset:0x2400
	ds_read_b64_tr_b16 v[100:101], v168 offset:0x2c00
	s_nop 0
	v_mfma_f32_32x32x16_bf16 v[66:81], v[82:85], v[102:105], v[66:81]
	ds_read_b64_tr_b16 v[102:103], v168 offset:0x3400
	ds_read_b64_tr_b16 v[104:105], v168 offset:0x3c00
	s_waitcnt lgkmcnt(6)
	s_nop 0
	v_mfma_f32_32x32x16_bf16 v[50:65], v[90:93], v[106:109], v[50:65]
	ds_read_b64_tr_b16 v[106:107], v168 offset:0x1600
	ds_read_b64_tr_b16 v[108:109], v168 offset:0x1e00
	v_mfma_f32_32x32x16_bf16 v[50:65], v[86:89], v[110:113], v[50:65]
	ds_read_b64_tr_b16 v[110:111], v168 offset:0x2600
	ds_read_b64_tr_b16 v[112:113], v168 offset:0x2e00
	v_mfma_f32_32x32x16_bf16 v[50:65], v[82:85], v[200:203], v[50:65]
	ds_read_b64_tr_b16 v[200:201], v168 offset:0x3600
	ds_read_b64_tr_b16 v[202:203], v168 offset:0x3e00
	s_waitcnt lgkmcnt(6)
	s_nop 0
	s_waitcnt lgkmcnt(0)
	v_mfma_f32_32x32x16_bf16 v[34:49], v[90:93], v[94:97], v[34:49]
	v_mfma_f32_32x32x16_bf16 v[18:33], v[90:93], v[106:109], v[18:33]
	v_mfma_f32_32x32x16_bf16 v[34:49], v[86:89], v[98:101], v[34:49]
	v_mfma_f32_32x32x16_bf16 v[18:33], v[86:89], v[110:113], v[18:33]
	v_mfma_f32_32x32x16_bf16 v[34:49], v[82:85], v[102:105], v[34:49]
	v_mfma_f32_32x32x16_bf16 v[18:33], v[82:85], v[200:203], v[18:33]
	s_branch .LBB0_530

; #define NA_VR(D) do { vl[D][0] = tr_read<v_rd_off(D, KS0, 0)>(vb); vh[D][0] = tr_read<v_rd_off(D, KS0, 1)>(vb); vl[D][1] = tr_read<v_rd_off(D, KS0 + 1, 0)>(vb); vh[D][1] = tr_read<v_rd_off(D, KS0 + 1, 1)>(vb); \
;     vl[D][2] = tr_read<v_rd_off(D, KS0 + 2, 0)>(vb); vh[D][2] = tr_read<v_rd_off(D, KS0 + 2, 1)>(vb); } while (0)
; template <int M> __device__ __forceinline__ void na_tile(f32x16 (&o)[4], float& m_reg, float& l_reg, f32x16& p0, f32x16& p1, int vb, const char* blane, int mbase, float* al_l, int r32, int hi) {
;   bf16x8 pa, pb, pc;
;   if constexpr (M == 0) { NA_BODY(p0, p1, 0, 0, 1, 4)  ATT_PK4(p0, 0, pa); ATT_PK4(p0, 8, pb); ATT_PK4(p1, 0, pc); }
;   else                  { NA_BODY(p1, p0, 12, 1, 0, 8) ATT_PK4(p0, 8, pa); ATT_PK4(p1, 0, pb); ATT_PK4(p1, 8, pc); }
;   constexpr int KS0 = (M == 0) ? 0 : 1;
;   s16x4 vl[4][3], vh[4][3];
;     ...
;   NA_VR(0); NA_VR(1); NA_PV(0, 6); NA_VR(2); NA_PV(1, 6); NA_VR(3); NA_PV(2, 6); NA_PV(3, 0);
.LBB0_555:
	v_sub_f32_e32 v100, v176, v171
	v_exp_f32_e32 v100, v100
	v_sub_f32_e32 v102, v175, v171
	v_exp_f32_e32 v102, v102
	v_sub_f32_e32 v99, v99, v171
	v_exp_f32_e32 v99, v99
	v_sub_f32_e32 v98, v98, v171
	v_exp_f32_e32 v98, v98
	v_sub_f32_e32 v97, v97, v171
	v_add_f32_e32 v101, 0, v100
	v_exp_f32_e32 v97, v97
	v_sub_f32_e32 v96, v96, v171
	v_add_f32_e32 v101, v102, v101
	v_exp_f32_e32 v96, v96
	v_sub_f32_e32 v95, v95, v171
	v_add_f32_e32 v101, v99, v101
	v_exp_f32_e32 v95, v95
	v_sub_f32_e32 v94, v94, v171
	v_add_f32_e32 v101, v98, v101
	v_exp_f32_e32 v94, v94
	v_sub_f32_e32 v93, v93, v171
	v_add_f32_e32 v101, v97, v101
	v_exp_f32_e32 v103, v93
	v_add_f32_e32 v101, v96, v101
	v_add_f32_e32 v101, v95, v101
	v_add_f32_e32 v101, v94, v101
	v_sub_f32_e32 v92, v92, v171
	v_add_f32_e32 v93, v103, v101
	v_exp_f32_e32 v101, v92
	v_sub_f32_e32 v91, v91, v171
	v_exp_f32_e32 v104, v91
	v_sub_f32_e32 v90, v90, v171
	v_exp_f32_e32 v105, v90
	v_sub_f32_e32 v89, v89, v171
	v_exp_f32_e32 v89, v89
	v_sub_f32_e32 v88, v88, v171
	v_add_f32_e32 v92, v101, v93
	v_exp_f32_e32 v88, v88
	v_sub_f32_e32 v87, v87, v171
	v_add_f32_e32 v91, v104, v92
	v_exp_f32_e32 v106, v87
	v_sub_f32_e32 v86, v86, v171
	v_add_f32_e32 v90, v105, v91
	v_exp_f32_e32 v107, v86
	v_sub_f32_e32 v82, v82, v171
	v_add_f32_e32 v90, v89, v90
	v_exp_f32_e32 v82, v82
	v_sub_f32_e32 v83, v83, v171
	v_add_f32_e32 v90, v88, v90
	v_exp_f32_e32 v83, v83
	v_sub_f32_e32 v84, v84, v171
	v_add_f32_e32 v87, v106, v90
	v_exp_f32_e32 v84, v84
	v_sub_f32_e32 v85, v85, v171
	v_add_f32_e32 v86, v107, v87
	v_exp_f32_e32 v85, v85
	v_add_f32_e32 v86, v82, v86
	v_add_f32_e32 v86, v83, v86
	v_add_f32_e32 v86, v84, v86
	v_add_f32_e32 v86, v85, v86
	v_mov_b32_e32 v87, v86
	s_nop 1
	v_permlane32_swap_b32_e32 v86, v87
	v_add_f32_e32 v86, v86, v87
	v_add_f32_e32 v169, v169, v86
	v_cvt_pk_bf16_f32 v90, v100, v102
	v_cvt_pk_bf16_f32 v91, v99, v98
	v_cvt_pk_bf16_f32 v92, v97, v96
	v_cvt_pk_bf16_f32 v93, v95, v94
	v_cvt_pk_bf16_f32 v86, v103, v101
	v_cvt_pk_bf16_f32 v87, v104, v105
	v_cvt_pk_bf16_f32 v88, v89, v88
	v_cvt_pk_bf16_f32 v89, v106, v107
	v_cvt_pk_bf16_f32 v82, v82, v83
	v_cvt_pk_bf16_f32 v83, v84, v85
	v_cvt_pk_bf16_f32 v84, v147, v147
	v_cvt_pk_bf16_f32 v85, v147, v147
	s_add_i32 s2, s55, -2
	s_cmp_lt_i32 s2, s83
	s_cselect_b64 s[48:49], -1, 0
	s_cmp_ge_i32 s2, s83
	s_cbranch_scc1 .Lna_stgB_done
	s_cmp_gt_i32 s2, s72
	s_waitcnt vmcnt(3)
	ds_write_b128 v165, v[114:117] offset:16384
	s_waitcnt vmcnt(1)
	ds_write_b128 v166, v[118:121] offset:16384
	ds_write_b128 v163, v[122:125] offset:49152
	s_waitcnt vmcnt(0)
	ds_write_b128 v164, v[126:129] offset:49152
	s_cbranch_scc1 .Lna_stgB_done
	v_lshl_add_u64 v[246:247], v[132:133], 0, v[146:147]
	v_add_co_u32_e32 v246, vcc, 0x1000, v246
	v_lshl_add_u64 v[254:255], v[130:131], 0, v[146:147]
	s_nop 0
	v_addc_co_u32_e32 v247, vcc, 0, v247, vcc
	v_add_co_u32_e32 v254, vcc, 0x1000, v254
	s_nop 1
	v_addc_co_u32_e32 v255, vcc, 0, v255, vcc
	global_load_dwordx4 v[114:117], v[246:247], off offset:2048
	global_load_dwordx4 v[122:125], v[246:247], off
	global_load_dwordx4 v[118:121], v[254:255], off offset:2048
	global_load_dwordx4 v[126:129], v[254:255], off
.Lna_stgB_done:
	ds_read_b64_tr_b16 v[94:95], v168 offset:0
	ds_read_b64_tr_b16 v[96:97], v168 offset:0x800
	ds_read_b64_tr_b16 v[98:99], v168 offset:0x1000
	ds_read_b64_tr_b16 v[100:101], v168 offset:0x1800
	ds_read_b64_tr_b16 v[102:103], v168 offset:0x2000
	ds_read_b64_tr_b16 v[104:105], v168 offset:0x2800
	ds_read_b64_tr_b16 v[106:107], v168 offset:0x200
	s_nop 0
	v_permlane32_swap_b32_e32 v90, v92
	v_permlane32_swap_b32_e32 v91, v93
	ds_read_b64_tr_b16 v[108:109], v168 offset:0xa00
	ds_read_b64_tr_b16 v[110:111], v168 offset:0x1200
	ds_read_b64_tr_b16 v[112:113], v168 offset:0x1a00
	ds_read_b64_tr_b16 v[176:177], v168 offset:0x2200
	ds_read_b64_tr_b16 v[178:179], v168 offset:0x2a00
	s_waitcnt lgkmcnt(6)
	v_permlane32_swap_b32_e32 v86, v88
	s_nop 0
	v_mfma_f32_32x32x16_bf16 v[66:81], v[90:93], v[94:97], v[66:81]
	v_permlane32_swap_b32_e32 v87, v89
	v_permlane32_swap_b32_e32 v82, v84
	v_permlane32_swap_b32_e32 v83, v85
	ds_read_b64_tr_b16 v[94:95], v168 offset:0x400
	v_mfma_f32_32x32x16_bf16 v[66:81], v[86:89], v[98:101], v[66:81]
	ds_read_b64_tr_b16 v[96:97], v168 offset:0xc00
	ds_read_b64_tr_b16 v[98:99], v168 offset:0x1400
	ds_read_b64_tr_b16 v[100:101], v168 offset:0x1c00
	s_nop 0
	v_mfma_f32_32x32x16_bf16 v[66:81], v[82:85], v[102:105], v[66:81]
	ds_read_b64_tr_b16 v[102:103], v168 offset:0x2400
	ds_read_b64_tr_b16 v[104:105], v168 offset:0x2c00
	s_waitcnt lgkmcnt(6)
	s_nop 0
	v_mfma_f32_32x32x16_bf16 v[50:65], v[90:93], v[106:109], v[50:65]
	ds_read_b64_tr_b16 v[106:107], v168 offset:0x600
	ds_read_b64_tr_b16 v[108:109], v168 offset:0xe00
	v_mfma_f32_32x32x16_bf16 v[50:65], v[86:89], v[110:113], v[50:65]
	ds_read_b64_tr_b16 v[110:111], v168 offset:0x1600
	ds_read_b64_tr_b16 v[112:113], v168 offset:0x1e00
	v_mfma_f32_32x32x16_bf16 v[50:65], v[82:85], v[176:179], v[50:65]
	ds_read_b64_tr_b16 v[176:177], v168 offset:0x2600
	ds_read_b64_tr_b16 v[178:179], v168 offset:0x2e00
	s_waitcnt lgkmcnt(6)
	s_nop 0
	s_waitcnt lgkmcnt(0)
	v_mfma_f32_32x32x16_bf16 v[34:49], v[90:93], v[94:97], v[34:49]
	v_mfma_f32_32x32x16_bf16 v[18:33], v[90:93], v[106:109], v[18:33]
	v_mfma_f32_32x32x16_bf16 v[34:49], v[86:89], v[98:101], v[34:49]
	v_mfma_f32_32x32x16_bf16 v[18:33], v[86:89], v[110:113], v[18:33]
	v_mfma_f32_32x32x16_bf16 v[34:49], v[82:85], v[102:105], v[34:49]
	v_mfma_f32_32x32x16_bf16 v[18:33], v[82:85], v[176:179], v[18:33]
	s_branch .LBB0_559
